# fast path v14 = v11 + merged s_waitcnt ladders in the attention fast block (56 -> 34 waits)
# speedup vs baseline: 1.0096x; 1.0096x over previous
; #define MFMA32(a, b, c) __builtin_amdgcn_mfma_f32_32x32x16_bf16((a), (b), (c), 0, 0, 0)
; DI unsigned pk_bf16(float lo, float hi) { f32x2 v = {lo, hi}; bf16v2 b = __builtin_convertvector(v, bf16v2); return __builtin_bit_cast(unsigned, b); }
; DI int crow(int r, int h) { return (r & 3) + 8 * (r >> 2) + 4 * h; }
; DI void attn_item(const Params& p, int g, int seq, int hd, int qt, int m, char* smem, int split_j, int sub) {
;     ...
;     bf16x8 kf[4], vf[2][4];
; #pragma unroll
;     for (int s = 0; s < 4; ++s) kf[s] = *(const bf16x8*)(Kb + l31 * 72 + s * 16 + h * 8);
; #pragma unroll
;     for (int s2 = 0; s2 < 2; ++s2)
; #pragma unroll
;       for (int dt = 0; dt < 4; ++dt) vf[s2][dt] = *(const bf16x8*)(Vb + (dt * 32 + l31) * 40 + s2 * 16 + h * 8);
;     __builtin_amdgcn_sched_barrier(0);
;     f32x16 X;
; #pragma unroll
;     for (int r = 0; r < 16; ++r) X[r] = 0.f;
; #pragma unroll
;     for (int s = 0; s < 4; ++s) X = MFMA32(kf[s], qf[s], X);
;     if (farL || farR) {
; #pragma unroll
;       for (int r = 0; r < 16; ++r) X[r] = __builtin_amdgcn_exp2f(X[r]);
;     } else {
;       const int rel0 = k0 - (qw0 + l31) + 128;
; #pragma unroll
;       for (int r = 0; r < 16; ++r) { int idx = rel0 + crow(r, h); idx = idx < 0 ? 0 : (idx > 256 ? 256 : idx); X[r] = __builtin_amdgcn_exp2f(X[r] + tab[idx]); }
;     }
;     bf16x8 pf[2];
; #pragma unroll
;     for (int s2 = 0; s2 < 2; ++s2) {
;       u32x4 w; w.x = pk_bf16(X[8 * s2], X[8 * s2 + 1]); w.y = pk_bf16(X[8 * s2 + 2], X[8 * s2 + 3]); w.z = pk_bf16(X[8 * s2 + 4], X[8 * s2 + 5]); w.w = pk_bf16(X[8 * s2 + 6], X[8 * s2 + 7]);
;       ls2 += (f32x2){X[8 * s2], X[8 * s2 + 1]}; ls2 += (f32x2){X[8 * s2 + 2], X[8 * s2 + 3]};
;       ls2 += (f32x2){X[8 * s2 + 4], X[8 * s2 + 5]}; ls2 += (f32x2){X[8 * s2 + 6], X[8 * s2 + 7]};
;       pf[s2] = __builtin_bit_cast(bf16x8, w);
;     }
; #pragma unroll
;     for (int s2 = 0; s2 < 2; ++s2)
; #pragma unroll
;       for (int dt = 0; dt < 4; ++dt) O[dt] = MFMA32(pf[s2], vf[s2][dt], O[dt]);
.Lat2_reads:
	ds_read_b128 v[64:67], v192
	ds_read_b128 v[80:83], v192 offset:32
	ds_read_b128 v[84:87], v192 offset:64
	ds_read_b128 v[88:91], v192 offset:96
	s_waitcnt lgkmcnt(3)
	v_mfma_f32_32x32x16_bf16 v[64:79], v[64:67], v[104:107], 0
	ds_read_b128 v[220:223], v192 offset:4608
	ds_read_b128 v[224:227], v192 offset:4640
	ds_read_b128 v[236:239], v192 offset:4672
	ds_read_b128 v[240:243], v192 offset:4704
	s_waitcnt lgkmcnt(6)
	v_mfma_f32_32x32x16_bf16 v[64:79], v[80:83], v[108:111], v[64:79]
	ds_read_b128 v[156:159], v244 offset:18432
	ds_read_b128 v[160:163], v244 offset:20992
	s_waitcnt lgkmcnt(7)
	v_mfma_f32_32x32x16_bf16 v[64:79], v[84:87], v[112:115], v[64:79]
	ds_read_b128 v[164:167], v244 offset:23552
	ds_read_b128 v[152:155], v244 offset:26112
	s_waitcnt lgkmcnt(8)
	v_mfma_f32_32x32x16_bf16 v[64:79], v[88:91], v[116:119], v[64:79]
	ds_read_b128 v[148:151], v244 offset:18464
	ds_read_b128 v[144:147], v244 offset:21024
	ds_read_b128 v[136:139], v244 offset:23584
	ds_read_b128 v[140:143], v244 offset:26144
	s_waitcnt lgkmcnt(8)
	v_mfma_f32_32x32x16_bf16 v[80:95], v[220:223], v[104:107], 0
	v_mfma_f32_32x32x16_bf16 v[80:95], v[224:227], v[108:111], v[80:95]
	v_exp_f32_e32 v64, v64
	v_exp_f32_e32 v65, v65
	v_exp_f32_e32 v66, v66
	v_exp_f32_e32 v67, v67
	v_exp_f32_e32 v68, v68
	v_exp_f32_e32 v69, v69
	v_mfma_f32_32x32x16_bf16 v[80:95], v[236:239], v[112:115], v[80:95]
	v_exp_f32_e32 v70, v70
	v_exp_f32_e32 v71, v71
	v_exp_f32_e32 v72, v72
	v_exp_f32_e32 v73, v73
	v_exp_f32_e32 v74, v74
	v_exp_f32_e32 v75, v75
	v_mfma_f32_32x32x16_bf16 v[80:95], v[240:243], v[116:119], v[80:95]
	v_exp_f32_e32 v76, v76
	v_exp_f32_e32 v77, v77
	v_exp_f32_e32 v78, v78
	v_exp_f32_e32 v79, v79
	v_cvt_pk_bf16_f32 v220, v64, v65
	v_cvt_pk_bf16_f32 v221, v66, v67
	v_cvt_pk_bf16_f32 v222, v68, v69
	v_cvt_pk_bf16_f32 v223, v70, v71
	v_cvt_pk_bf16_f32 v224, v72, v73
	v_cvt_pk_bf16_f32 v225, v74, v75
	v_cvt_pk_bf16_f32 v226, v76, v77
	v_cvt_pk_bf16_f32 v227, v78, v79
	s_waitcnt lgkmcnt(0)
	v_mfma_f32_32x32x16_bf16 v[48:63], v[220:223], v[156:159], v[48:63]
	ds_read_b128 v[156:159], v244 offset:28672
	v_exp_f32_e32 v80, v80
	v_exp_f32_e32 v81, v81
	v_exp_f32_e32 v82, v82
	v_mfma_f32_32x32x16_bf16 v[32:47], v[220:223], v[160:163], v[32:47]
	ds_read_b128 v[160:163], v244 offset:31232
	v_exp_f32_e32 v83, v83
	v_exp_f32_e32 v84, v84
	v_exp_f32_e32 v85, v85
	v_mfma_f32_32x32x16_bf16 v[16:31], v[220:223], v[164:167], v[16:31]
	ds_read_b128 v[164:167], v244 offset:33792
	v_exp_f32_e32 v86, v86
	v_exp_f32_e32 v87, v87
	v_exp_f32_e32 v88, v88
	v_mfma_f32_32x32x16_bf16 v[0:15], v[220:223], v[152:155], v[0:15]
	ds_read_b128 v[152:155], v244 offset:36352
	v_exp_f32_e32 v89, v89
	v_exp_f32_e32 v90, v90
	v_exp_f32_e32 v91, v91
	v_mfma_f32_32x32x16_bf16 v[48:63], v[224:227], v[148:151], v[48:63]
	ds_read_b128 v[148:151], v244 offset:28704
	v_exp_f32_e32 v92, v92
	v_exp_f32_e32 v93, v93
	v_exp_f32_e32 v94, v94
	v_exp_f32_e32 v95, v95
	v_mfma_f32_32x32x16_bf16 v[32:47], v[224:227], v[144:147], v[32:47]
	ds_read_b128 v[144:147], v244 offset:31264
	v_cvt_pk_bf16_f32 v236, v80, v81
	v_cvt_pk_bf16_f32 v237, v82, v83
	v_cvt_pk_bf16_f32 v238, v84, v85
	v_add_f32_e32 v246, v66, v70
	v_add_f32_e32 v247, v67, v71
	v_add_f32_e32 v186, v186, v64
	v_add_f32_e32 v187, v187, v65
	v_mfma_f32_32x32x16_bf16 v[16:31], v[224:227], v[136:139], v[16:31]
	ds_read_b128 v[136:139], v244 offset:33824
	v_cvt_pk_bf16_f32 v239, v86, v87
	v_cvt_pk_bf16_f32 v240, v88, v89
	v_cvt_pk_bf16_f32 v241, v90, v91
	v_add_f32_e32 v246, v246, v74
	v_add_f32_e32 v247, v247, v75
	v_add_f32_e32 v186, v186, v68
	v_add_f32_e32 v187, v187, v69
	v_mfma_f32_32x32x16_bf16 v[0:15], v[224:227], v[140:143], v[0:15]
	ds_read_b128 v[140:143], v244 offset:36384
	v_cvt_pk_bf16_f32 v242, v92, v93
	v_cvt_pk_bf16_f32 v243, v94, v95
	v_add_f32_e32 v246, v246, v78
	v_add_f32_e32 v247, v247, v79
	v_add_f32_e32 v186, v186, v72
	v_add_f32_e32 v187, v187, v73
	s_andn2_b64 vcc, exec, s[8:9]
	s_cbranch_vccnz .Lat2_pvplain
	s_add_i32 s10, s15, 1
	s_cmp_lt_u32 s10, s73
	s_cbranch_scc0 .Lat2_pvw
; #define MFMA32(a, b, c) __builtin_amdgcn_mfma_f32_32x32x16_bf16((a), (b), (c), 0, 0, 0)
; DI unsigned pk_bf16(float lo, float hi) { f32x2 v = {lo, hi}; bf16v2 b = __builtin_convertvector(v, bf16v2); return __builtin_bit_cast(unsigned, b); }
; DI void attn_item(const Params& p, int g, int seq, int hd, int qt, int m, char* smem, int split_j, int sub) {
;     ...
;     bf16x8 pf[2];
; #pragma unroll
;     for (int s2 = 0; s2 < 2; ++s2) {
;       u32x4 w; w.x = pk_bf16(X[8 * s2], X[8 * s2 + 1]); w.y = pk_bf16(X[8 * s2 + 2], X[8 * s2 + 3]); w.z = pk_bf16(X[8 * s2 + 4], X[8 * s2 + 5]); w.w = pk_bf16(X[8 * s2 + 6], X[8 * s2 + 7]);
;       ls2 += (f32x2){X[8 * s2], X[8 * s2 + 1]}; ls2 += (f32x2){X[8 * s2 + 2], X[8 * s2 + 3]};
;       ls2 += (f32x2){X[8 * s2 + 4], X[8 * s2 + 5]}; ls2 += (f32x2){X[8 * s2 + 6], X[8 * s2 + 7]};
;       pf[s2] = __builtin_bit_cast(bf16x8, w);
;     }
; #pragma unroll
;     for (int s2 = 0; s2 < 2; ++s2)
; #pragma unroll
;       for (int dt = 0; dt < 4; ++dt) O[dt] = MFMA32(pf[s2], vf[s2][dt], O[dt]);
;   };
;   load_tile(0, rkA, rvA0, rvA1);
;   load_tile(1, rkB, rvB0, rvB1);
;   __syncthreads();
;   store_tile(0, rkA, rvA0, rvA1);
;   store_tile(1, rkB, rvB0, rvB1);
;   __syncthreads();
;   for (int it = 0; it < npairs; ++it) {
;     const int set = it & 1;
;     if (it + 1 < npairs) { load_tile(2 * it + 2, rkA, rvA0, rvA1); load_tile(2 * it + 3, rkB, rvB0, rvB1); }
;     compute(2 * it, 2 * set);
;     compute(2 * it + 1, 2 * set + 1);
;     if (it + 1 < npairs) { store_tile(2 * (set ^ 1), rkA, rvA0, rvA1); store_tile(2 * (set ^ 1) + 1, rkB, rvB0, rvB1); }
;     __syncthreads();
	s_xor_b32 s7, s16, 2
	s_mul_i32 s8, s7, 0x2800
	s_add_i32 s8, s8, 32
	s_mulk_i32 s7, 0x1200
	v_add_u32_e32 v192, s7, v169
	v_add3_u32 v244, s8, v189, v190
	s_addk_i32 s8, 0x2800
	s_add_i32 s13, s13, 64
	s_add_i32 s6, s6, 2
	s_mov_b32 s15, s10
	s_mov_b64 s[20:21], 0x1000
	s_waitcnt lgkmcnt(6)
	v_mfma_f32_32x32x16_bf16 v[48:63], v[236:239], v[156:159], v[48:63]
	s_waitcnt vmcnt(5)
	ds_write_b128 v192, v[96:99]
	s_add_i32 s50, s6, -1
	s_lshl_b64 s[10:11], s[50:51], 12
	v_lshl_add_u64 v[220:221], v[172:173], 0, s[10:11]
	v_add_f32_e32 v186, v186, v76
	v_add_f32_e32 v187, v187, v77
	v_mfma_f32_32x32x16_bf16 v[32:47], v[236:239], v[160:163], v[32:47]
	s_waitcnt vmcnt(4)
	ds_write_b128 v244, v[100:103] offset:18432
	global_load_dwordx4 v[96:99], v[220:221], off
	s_lshl_b64 s[10:11], s[50:51], 13
	v_lshl_add_u64 v[222:223], v[170:171], 0, s[10:11]
	v_add_f32_e32 v186, v186, v246
	v_add_f32_e32 v187, v187, v247
	s_waitcnt lgkmcnt(6)
	v_mfma_f32_32x32x16_bf16 v[16:31], v[236:239], v[164:167], v[16:31]
	s_waitcnt vmcnt(4)
	ds_write_b128 v244, v[120:123] offset:23552
	global_load_dwordx4 v[100:103], v[222:223], off
	v_lshl_add_u64 v[224:225], v[222:223], 0, s[20:21]
	v_add_f32_e32 v246, v82, v86
	v_add_f32_e32 v247, v83, v87
	v_add_f32_e32 v186, v186, v80
	v_mfma_f32_32x32x16_bf16 v[0:15], v[236:239], v[152:155], v[0:15]
	s_waitcnt vmcnt(4)
	ds_write_b128 v192, v[124:127] offset:4608
	global_load_dwordx4 v[120:123], v[224:225], off
	s_mov_b32 s7, s51
	s_lshl_b64 s[10:11], s[6:7], 12
	v_lshl_add_u64 v[220:221], v[172:173], 0, s[10:11]
	v_add_f32_e32 v187, v187, v81
	v_add_f32_e32 v246, v246, v90
	v_add_f32_e32 v247, v247, v91
	s_waitcnt lgkmcnt(6)
	v_mfma_f32_32x32x16_bf16 v[48:63], v[240:243], v[148:151], v[48:63]
	v_add3_u32 v192, s8, v189, v190
	s_waitcnt vmcnt(4)
	ds_write_b128 v192, v[128:131] offset:18432
	global_load_dwordx4 v[124:127], v[220:221], off
	s_lshl_b64 s[10:11], s[6:7], 13
	v_lshl_add_u64 v[222:223], v[170:171], 0, s[10:11]
	v_add_f32_e32 v186, v186, v84
	v_add_f32_e32 v187, v187, v85
	v_add_f32_e32 v246, v246, v94
	v_mfma_f32_32x32x16_bf16 v[32:47], v[240:243], v[144:147], v[32:47]
	s_waitcnt vmcnt(4)
	ds_write_b128 v192, v[132:135] offset:23552
	global_load_dwordx4 v[128:131], v[222:223], off
	v_lshl_add_u64 v[224:225], v[222:223], 0, s[20:21]
	v_add_f32_e32 v247, v247, v95
	v_add_f32_e32 v186, v186, v88
	v_add_f32_e32 v187, v187, v89
	s_waitcnt lgkmcnt(6)
	v_mfma_f32_32x32x16_bf16 v[16:31], v[240:243], v[136:139], v[16:31]
	global_load_dwordx4 v[132:135], v[224:225], off
	v_add_f32_e32 v186, v186, v92
	v_add_f32_e32 v187, v187, v93
	s_add_i32 s7, s14, s13
	s_cmpk_lt_i32 s7, 0xff42
	s_cselect_b32 s19, 1, 0
	s_cmpk_gt_i32 s7, 0x9e
	s_cselect_b32 s50, 1, 0
	s_cmp_eq_u32 s17, 2
	s_cselect_b32 s50, s50, 0
	s_or_b32 s19, s19, s50
	v_mfma_f32_32x32x16_bf16 v[0:15], v[240:243], v[140:143], v[0:15]
	v_add_f32_e32 v186, v186, v246
	v_add_f32_e32 v187, v187, v247
	s_mov_b64 s[8:9], -1
	s_add_i32 s10, s6, -3
	s_and_b32 s16, s10, 2
	s_mul_i32 s10, s16, 0x1200
	s_mul_i32 s18, s16, 0x2800
	v_add_u32_e32 v192, s10, v191
	v_add_u32_e32 v244, s18, v196
	s_cmp_lg_u32 s19, 0
	s_waitcnt lgkmcnt(0)
	s_barrier
	s_cbranch_scc1 .Lat2_reads
	s_branch .LBB0_319
.Lat2_pvw:
	s_xor_b32 s7, s16, 2
	s_mul_i32 s8, s7, 0x2800
	s_add_i32 s8, s8, 32
	s_mulk_i32 s7, 0x1200
	v_add_u32_e32 v192, s7, v169
	v_add3_u32 v244, s8, v189, v190
	s_addk_i32 s8, 0x2800
	s_waitcnt lgkmcnt(6)
	v_mfma_f32_32x32x16_bf16 v[48:63], v[236:239], v[156:159], v[48:63]
	s_waitcnt vmcnt(5)
	ds_write_b128 v192, v[96:99]
	v_add_f32_e32 v186, v186, v76
	v_add_f32_e32 v187, v187, v77
	v_mfma_f32_32x32x16_bf16 v[32:47], v[236:239], v[160:163], v[32:47]
	s_waitcnt vmcnt(4)
	ds_write_b128 v244, v[100:103] offset:18432
	v_add_f32_e32 v186, v186, v246
	v_add_f32_e32 v187, v187, v247
	s_waitcnt lgkmcnt(6)
	v_mfma_f32_32x32x16_bf16 v[16:31], v[236:239], v[164:167], v[16:31]
	s_waitcnt vmcnt(3)
	ds_write_b128 v244, v[120:123] offset:23552
	v_add_f32_e32 v246, v82, v86
	v_add_f32_e32 v247, v83, v87
	v_add_f32_e32 v186, v186, v80
	v_mfma_f32_32x32x16_bf16 v[0:15], v[236:239], v[152:155], v[0:15]
	s_waitcnt vmcnt(2)
	ds_write_b128 v192, v[124:127] offset:4608
	v_add_f32_e32 v187, v187, v81
	v_add_f32_e32 v246, v246, v90
	v_add_f32_e32 v247, v247, v91
	s_waitcnt lgkmcnt(6)
	v_mfma_f32_32x32x16_bf16 v[48:63], v[240:243], v[148:151], v[48:63]
	v_add3_u32 v192, s8, v189, v190
	s_waitcnt vmcnt(1)
	ds_write_b128 v192, v[128:131] offset:18432
	v_add_f32_e32 v186, v186, v84
	v_add_f32_e32 v187, v187, v85
	v_add_f32_e32 v246, v246, v94
	v_mfma_f32_32x32x16_bf16 v[32:47], v[240:243], v[144:147], v[32:47]
	s_waitcnt vmcnt(0)
	ds_write_b128 v192, v[132:135] offset:23552
	v_add_f32_e32 v247, v247, v95
	v_add_f32_e32 v186, v186, v88
	v_add_f32_e32 v187, v187, v89
	s_waitcnt lgkmcnt(6)
	v_mfma_f32_32x32x16_bf16 v[16:31], v[240:243], v[136:139], v[16:31]
	v_add_f32_e32 v186, v186, v92
	v_add_f32_e32 v187, v187, v93
	v_mfma_f32_32x32x16_bf16 v[0:15], v[240:243], v[140:143], v[0:15]
	v_add_f32_e32 v186, v186, v246
	v_add_f32_e32 v187, v187, v247
	s_branch .Lat2_bot
.Lat2_pvplain:
	s_waitcnt lgkmcnt(6)
	v_mfma_f32_32x32x16_bf16 v[48:63], v[236:239], v[156:159], v[48:63]
	v_add_f32_e32 v186, v186, v76
	v_add_f32_e32 v187, v187, v77
	v_mfma_f32_32x32x16_bf16 v[32:47], v[236:239], v[160:163], v[32:47]
	v_add_f32_e32 v186, v186, v246
	v_add_f32_e32 v187, v187, v247
	s_waitcnt lgkmcnt(4)
	v_mfma_f32_32x32x16_bf16 v[16:31], v[236:239], v[164:167], v[16:31]
	v_add_f32_e32 v246, v82, v86
	v_add_f32_e32 v247, v83, v87
	v_add_f32_e32 v186, v186, v80
	v_mfma_f32_32x32x16_bf16 v[0:15], v[236:239], v[152:155], v[0:15]
	v_add_f32_e32 v187, v187, v81
	v_add_f32_e32 v246, v246, v90
	v_add_f32_e32 v247, v247, v91
	s_waitcnt lgkmcnt(2)
	v_mfma_f32_32x32x16_bf16 v[48:63], v[240:243], v[148:151], v[48:63]
	v_add_f32_e32 v186, v186, v84
	v_add_f32_e32 v187, v187, v85
	v_add_f32_e32 v246, v246, v94
	v_mfma_f32_32x32x16_bf16 v[32:47], v[240:243], v[144:147], v[32:47]
	v_add_f32_e32 v247, v247, v95
	v_add_f32_e32 v186, v186, v88
	v_add_f32_e32 v187, v187, v89
	s_waitcnt lgkmcnt(0)
	v_mfma_f32_32x32x16_bf16 v[16:31], v[240:243], v[136:139], v[16:31]
	v_add_f32_e32 v186, v186, v92
	v_add_f32_e32 v187, v187, v93
	v_mfma_f32_32x32x16_bf16 v[0:15], v[240:243], v[140:143], v[0:15]
	v_add_f32_e32 v186, v186, v246
	v_add_f32_e32 v187, v187, v247
